# cache warm-up of the mixer-output weights (2 MiB, converted ~0.9 ms earlier) by one fire-and-forget LDS-DMA per wave at the start of phase 7, before the mixer-output GEMM streams them
# speedup vs baseline: 1.0066x; 1.0019x over previous
.LBB0_757:
	s_cmp_lt_i32 s88, 8
	s_cselect_b64 s[0:1], -1, 0
	s_and_b64 s[38:39], s[0:1], s[2:3]
	s_andn2_b64 vcc, exec, s[38:39]
	s_cbranch_vccnz .LBB0_1061
	s_and_b32 s100, s66, 31
	s_lshl_b32 s100, s100, 9
	v_add_u32_e32 v254, s100, v0
	v_lshlrev_b32_e32 v254, 7, v254
	v_add_u32_e32 v254, 0x2a00000, v254
	s_mov_b32 s100, m0
	s_mov_b32 m0, 0x20400
	s_nop 0
	global_load_lds_dwordx4 v254, s[78:79]
	s_mov_b32 m0, s100
	s_cmpk_eq_i32 s68, 0x100
	s_mov_b64 s[0:1], -1
	s_cbranch_scc1 .LBB0_910
	s_mov_b32 s85, s75
	s_cmpk_gt_i32 s66, 0x1ff
	s_cbranch_scc1 .LBB0_909
	v_readlane_b32 s4, v253, 0
	s_lshr_b32 s2, s4, 7
	v_lshrrev_b32_e32 v11, 5, v177
	s_bfe_u32 s0, s4, 0x10006
	s_lshl_b32 s1, s2, 14
	v_lshlrev_b32_e32 v10, 2, v11
	v_and_b32_e32 v1, 31, v0
	s_add_i32 s3, s1, 0
	s_lshl_b32 s60, s0, 5
	v_or_b32_e32 v12, 2, v10
	s_bitcmp1_b32 s4, 6
	v_cmp_gt_u32_e64 s[4:5], v12, v1
	v_or_b32_e32 v12, 3, v10
	v_cmp_gt_u32_e64 s[6:7], v12, v1
	v_or_b32_e32 v12, 8, v10
	v_cmp_gt_u32_e64 s[8:9], v12, v1
	v_or_b32_e32 v12, 9, v10
	v_cmp_gt_u32_e64 s[10:11], v12, v1
	v_or_b32_e32 v12, 10, v10
	v_cmp_gt_u32_e64 s[12:13], v12, v1
	v_or_b32_e32 v12, 11, v10
	v_cmp_gt_u32_e64 s[14:15], v12, v1
	v_or_b32_e32 v12, 16, v10
	v_cmp_gt_u32_e64 s[16:17], v12, v1
	v_or_b32_e32 v12, 17, v10
	v_cmp_gt_u32_e64 s[18:19], v12, v1
	v_or_b32_e32 v12, 18, v10
	v_cmp_gt_u32_e64 s[20:21], v12, v1
	v_or_b32_e32 v12, 19, v10
	v_cmp_gt_u32_e64 s[22:23], v12, v1
	v_or_b32_e32 v12, 24, v10
	v_lshl_or_b32 v3, s0, 6, v177
	v_cmp_gt_u32_e64 s[24:25], v12, v1
	v_or_b32_e32 v12, 25, v10
	v_lshrrev_b32_e32 v4, 4, v3
	v_cmp_gt_u32_e64 s[26:27], v12, v1
	v_or_b32_e32 v12, 26, v10
	v_mul_u32_u24_e32 v104, 0x1800, v4
	v_lshlrev_b32_e32 v4, 10, v0
	v_lshlrev_b32_e32 v7, 4, v0
	v_cmp_gt_u32_e64 s[28:29], v12, v1
	v_lshlrev_b32_e32 v12, 1, v177
	v_and_b32_e32 v4, 0x3000, v4
	v_and_b32_e32 v6, 48, v7
	v_and_b32_e32 v12, 32, v12
	v_add3_u32 v9, s3, v4, v6
	s_cselect_b64 s[64:65], -1, 0
	v_add_u32_e32 v12, s3, v12
	s_lshl_b32 s3, s96, 13
	v_cmp_gt_u32_e64 s[0:1], v10, v1
	v_cmp_ge_u32_e64 s[36:37], v10, v1
	v_or_b32_e32 v10, 27, v10
	s_add_i32 s3, s3, 0
	v_lshlrev_b32_e32 v5, 3, v177
	v_or_b32_e32 v4, s60, v1
	v_lshlrev_b32_e32 v6, 3, v11
	v_mul_u32_u24_e32 v8, 0xc00, v1
	v_cmp_gt_u32_e64 s[30:31], v10, v1
	v_lshlrev_b32_e32 v10, 6, v1
	v_lshlrev_b32_e32 v13, 8, v11
	s_add_i32 s3, s3, 0x10000
	v_lshlrev_b32_e32 v11, 10, v11
	v_lshlrev_b32_e32 v1, 1, v1
	v_and_b32_e32 v2, 0x78, v5
	v_lshrrev_b32_e32 v106, 4, v177
	v_and_b32_e32 v5, 24, v5
	v_add3_u32 v1, s3, v11, v1
	v_lshlrev_b32_e32 v11, 3, v0
	v_add3_u32 v5, v12, v5, v13
	v_and_b32_e32 v12, 0x78, v11
	v_readlane_b32 s40, v253, 20
	v_or_b32_e32 v11, s60, v106
	v_readlane_b32 s34, v252, 4
	v_mul_u32_u24_e32 v110, 0x1800, v11
	v_lshl_add_u32 v11, v12, 1, s3
	s_mov_b32 s40, s34
	s_lshl_b32 s3, s34, 15
	s_lshl_b32 s34, s2, 13
	v_lshlrev_b32_e32 v3, 2, v3
	v_or_b32_e32 v112, 4, v106
	v_or_b32_e32 v114, 8, v106
	v_or_b32_e32 v116, 12, v106
	v_or_b32_e32 v118, 16, v106
	v_or_b32_e32 v120, 20, v106
	v_or_b32_e32 v122, 24, v106
	v_or_b32_e32 v124, 28, v106
	s_add_i32 s58, s3, s34
	s_lshl_b32 s3, s40, 8
	s_lshl_b32 s34, s2, 6
	s_mov_b32 s57, 0
	v_mov_b32_e32 v103, 0
	v_and_b32_e32 v3, 0x1c0, v3
	v_mul_u32_u24_e32 v4, 0xc00, v4
	v_and_b32_e32 v7, 0xc0, v7
	v_lshlrev_b32_e32 v102, 2, v12
	v_readlane_b32 s50, v253, 30
	v_readlane_b32 s51, v253, 31
	v_lshlrev_b32_e32 v13, 8, v106
	v_lshlrev_b32_e32 v14, 8, v112
	v_lshlrev_b32_e32 v15, 8, v114
	v_lshlrev_b32_e32 v16, 8, v116
	v_lshlrev_b32_e32 v17, 8, v118
	v_lshlrev_b32_e32 v18, 8, v120
	v_lshlrev_b32_e32 v19, 8, v122
	v_lshlrev_b32_e32 v20, 8, v124
	s_add_i32 s72, s3, s34
	s_lshl_b32 s3, s40, 2
	v_lshlrev_b32_e32 v126, 1, v2
	v_mbcnt_lo_u32_b32 v2, -1, 0
	v_mov_b32_e32 v105, v103
	v_lshl_add_u64 v[108:109], s[50:51], 0, v[102:103]
	v_mov_b32_e32 v111, v103
	s_mov_b32 s61, s57
	s_lshl_b32 s59, s68, 15
	s_lshl_b32 s73, s68, 8
	s_add_i32 s74, s2, s3
	s_lshl_b32 s75, s68, 2
	s_movk_i32 s76, 0x1000
	s_mov_b32 s77, 0xd000
	s_mov_b32 s78, 0x19000
	s_mov_b32 s79, 0x25000
	v_add_u32_e32 v107, v9, v3
	v_lshlrev_b32_e32 v102, 1, v4
	v_lshlrev_b32_e32 v128, 1, v6
	v_lshlrev_b32_e32 v130, 1, v8
	v_lshlrev_b32_e32 v132, 1, v10
	v_mbcnt_hi_u32_b32 v113, -1, v2
	v_mov_b32_e32 v115, 0x358637bd
	s_mov_b32 s80, 0xf800000
	v_mov_b32_e32 v117, 0x260
	s_movk_i32 s81, 0x7fff
	v_lshlrev_b32_e32 v134, 1, v12
	v_add_u32_e32 v119, v11, v13
	s_mov_b32 s82, 0xffff0000
	s_mov_b32 s83, 0x14800000
	v_add_u32_e32 v121, v11, v14
	v_add_u32_e32 v123, v11, v15
	v_add_u32_e32 v125, v11, v16
	v_add_u32_e32 v136, v11, v17
	v_add_u32_e32 v137, v11, v18
	v_add_u32_e32 v138, v11, v19
	v_add_u32_e32 v139, v11, v20
	v_mov_b32_e32 v127, v103
	v_add_u32_e32 v140, v5, v7
	s_mov_b32 s84, s40
	v_readlane_b32 s41, v253, 21
	v_readlane_b32 s42, v253, 22
	v_readlane_b32 s43, v253, 23
	v_readlane_b32 s44, v253, 24
	v_readlane_b32 s45, v253, 25
	v_readlane_b32 s46, v253, 26
	v_readlane_b32 s47, v253, 27
	v_readlane_b32 s48, v253, 28
	v_readlane_b32 s49, v253, 29
	v_readlane_b32 s52, v253, 32
	v_readlane_b32 s53, v253, 33
	v_readlane_b32 s54, v253, 34
	v_readlane_b32 s55, v253, 35
	v_readlane_b32 s35, v252, 5
	s_branch .LBB0_762
